# v16 + grid-barrier acquire moved: each workgroup leader issues its buffer_inv sc1 right after its arrival atomic returns (overlaps the spin), instead of after the generation flip
# speedup vs baseline: 1.1546x; 1.1546x over previous
; __device__ __forceinline__ unsigned xb_ld(unsigned* p)              { return __hip_atomic_load(p, __ATOMIC_RELAXED, __HIP_MEMORY_SCOPE_AGENT); }
; __device__ __forceinline__ unsigned xb_add(unsigned* p, unsigned v) { return __hip_atomic_fetch_add(p, v, __ATOMIC_RELAXED, __HIP_MEMORY_SCOPE_AGENT); }
; #define XB_SPIN(cond, bar) do { unsigned _sp = 0; while (cond) { __builtin_amdgcn_s_sleep(1); \
;     if ((++_sp & 255u) == 0u) { if (xb_ld(&(bar)[XB_TMO])) break; if (_sp > XB_SPIN_CAP) { atomicAdd(&(bar)[XB_TMO], 1u); break; } } } } while (0)
; __device__ __forceinline__ void xcd_barrier(const XcdBarrier& b) {
;     ...
;         const unsigned old = xb_add(&bar[XB_XSUB(b.x)], 1u);
;         const unsigned gen = old / nloc;
;         if (old + 1u == (gen + 1u) * nloc) {
;             __builtin_amdgcn_fence(__ATOMIC_RELEASE, "agent");
;             asm volatile("s_waitcnt vmcnt(0)" ::: "memory");
;             const unsigned og = xb_add(&bar[XB_TOP], 1u);
;             const unsigned tg = og / nx;
;             if (og + 1u == (tg + 1u) * nx) xb_add(&bar[XB_TOPGEN], 1u);
;             else XB_SPIN(xb_ld(&bar[XB_TOPGEN]) == tg, bar);
;             __builtin_amdgcn_fence(__ATOMIC_ACQUIRE, "agent");
;             xb_add(&bar[XB_XGEN(b.x)], 1u);
;             asm volatile("s_waitcnt vmcnt(0)" ::: "memory");
;         } else {
;             XB_SPIN(xb_ld(&bar[XB_XGEN(b.x)]) == gen, bar);
.LBB0_586:
	s_lshl_b32 s24, s20, 6
	s_add_i32 s8, s24, 0x500
	s_mov_b32 s9, 0
	s_lshl_b64 s[6:7], s[8:9], 2
	s_add_u32 s6, s4, s6
	s_addc_u32 s7, s5, s7
	v_mov_b32_e32 v4, 0
	v_mov_b32_e32 v2, 1
	global_atomic_add v5, v4, v2, s[6:7] sc0
	v_cvt_f32_u32_e32 v2, v3
	v_sub_u32_e32 v6, 0, v3
	v_rcp_iflag_f32_e32 v2, v2
	s_nop 0
	v_mul_f32_e32 v2, 0x4f7ffffe, v2
	v_cvt_u32_f32_e32 v2, v2
	v_mul_lo_u32 v6, v6, v2
	v_mul_hi_u32 v6, v2, v6
	v_add_u32_e32 v2, v2, v6
	s_waitcnt vmcnt(0)
	buffer_inv sc1
	v_mul_hi_u32 v2, v5, v2
	v_mul_lo_u32 v6, v2, v3
	v_sub_u32_e32 v6, v5, v6
	v_add_u32_e32 v7, 1, v2
	v_cmp_ge_u32_e32 vcc, v6, v3
	v_add_u32_e32 v5, 1, v5
	s_nop 0
	v_cndmask_b32_e32 v2, v2, v7, vcc
	v_sub_u32_e32 v7, v6, v3
	v_cndmask_b32_e32 v6, v6, v7, vcc
	v_add_u32_e32 v7, 1, v2
	v_cmp_ge_u32_e32 vcc, v6, v3
	s_nop 1
	v_cndmask_b32_e32 v2, v2, v7, vcc
	v_mul_lo_u32 v6, v3, v2
	v_add_u32_e32 v3, v6, v3
	v_cmp_ne_u32_e32 vcc, v5, v3
	s_and_saveexec_b64 s[6:7], vcc
	s_xor_b64 s[6:7], exec, s[6:7]
	s_cbranch_execz .LBB0_600
	s_add_i32 s8, s24, 0x900
	s_lshl_b64 s[8:9], s[8:9], 2
	s_add_u32 s10, s4, s8
	s_addc_u32 s11, s5, s9
	s_waitcnt lgkmcnt(0)
	global_load_dword v1, v4, s[10:11] sc1
	s_waitcnt vmcnt(0)
	v_cmp_eq_u32_e32 vcc, v1, v2
	s_and_saveexec_b64 s[8:9], vcc
	s_cbranch_execz .LBB0_599
	s_mov_b32 s22, 1
	s_mov_b64 s[12:13], 0
	v_mov_b32_e32 v1, 0
	s_branch .LBB0_590

; __device__ __forceinline__ unsigned xb_ld(unsigned* p)              { return __hip_atomic_load(p, __ATOMIC_RELAXED, __HIP_MEMORY_SCOPE_AGENT); }
; #define XB_SPIN(cond, bar) do { unsigned _sp = 0; while (cond) { __builtin_amdgcn_s_sleep(1); \
;     if ((++_sp & 255u) == 0u) { if (xb_ld(&(bar)[XB_TMO])) break; if (_sp > XB_SPIN_CAP) { atomicAdd(&(bar)[XB_TMO], 1u); break; } } } } while (0)
; __device__ __forceinline__ void xcd_barrier(const XcdBarrier& b) {
;     ...
;             XB_SPIN(xb_ld(&bar[XB_XGEN(b.x)]) == gen, bar);
;             __builtin_amdgcn_fence(__ATOMIC_ACQUIRE, "agent");
;             asm volatile("s_waitcnt vmcnt(0)" ::: "memory");
.LBB0_599:
	s_or_b64 exec, exec, s[8:9]
	s_waitcnt vmcnt(0)
	s_waitcnt vmcnt(0)

; __device__ __forceinline__ unsigned xb_add(unsigned* p, unsigned v) { return __hip_atomic_fetch_add(p, v, __ATOMIC_RELAXED, __HIP_MEMORY_SCOPE_AGENT); }
; __device__ __forceinline__ void xcd_barrier(const XcdBarrier& b) {
;     ...
;             __builtin_amdgcn_fence(__ATOMIC_ACQUIRE, "agent");
;             xb_add(&bar[XB_XGEN(b.x)], 1u);
;             asm volatile("s_waitcnt vmcnt(0)" ::: "memory");
.LBB0_617:
	s_or_b64 exec, exec, s[6:7]
	s_add_i32 s6, s24, 0x900
	s_mov_b32 s7, 0
	s_lshl_b64 s[6:7], s[6:7], 2
	s_add_u32 s4, s4, s6
	s_addc_u32 s5, s5, s7
	v_mov_b32_e32 v1, 0
	v_mov_b32_e32 v2, 1
	s_waitcnt vmcnt(0)
	global_atomic_add v1, v2, s[4:5]
	s_waitcnt vmcnt(0)

; __device__ __forceinline__ unsigned xb_add(unsigned* p, unsigned v) { return __hip_atomic_fetch_add(p, v, __ATOMIC_RELAXED, __HIP_MEMORY_SCOPE_AGENT); }
; __device__ __forceinline__ void xcd_barrier(const XcdBarrier& b) {
;     ...
;             __builtin_amdgcn_fence(__ATOMIC_ACQUIRE, "agent");
;             xb_add(&bar[XB_XGEN(b.x)], 1u);
;             asm volatile("s_waitcnt vmcnt(0)" ::: "memory");
.LBB0_620:
	s_or_b64 exec, exec, s[4:5]
	s_add_i32 s92, s22, 0x900
	s_lshl_b64 s[4:5], s[92:93], 2
	s_add_u32 s2, s2, s4
	s_addc_u32 s3, s3, s5
	s_waitcnt vmcnt(0)
	global_atomic_add v35, v228, s[2:3]
	s_waitcnt vmcnt(0)

; __device__ __forceinline__ unsigned xb_ld(unsigned* p)              { return __hip_atomic_load(p, __ATOMIC_RELAXED, __HIP_MEMORY_SCOPE_AGENT); }
; __device__ __forceinline__ unsigned xb_add(unsigned* p, unsigned v) { return __hip_atomic_fetch_add(p, v, __ATOMIC_RELAXED, __HIP_MEMORY_SCOPE_AGENT); }
; #define XB_SPIN(cond, bar) do { unsigned _sp = 0; while (cond) { __builtin_amdgcn_s_sleep(1); \
;     if ((++_sp & 255u) == 0u) { if (xb_ld(&(bar)[XB_TMO])) break; if (_sp > XB_SPIN_CAP) { atomicAdd(&(bar)[XB_TMO], 1u); break; } } } } while (0)
; __device__ __forceinline__ void xcd_barrier(const XcdBarrier& b) {
;     ...
;         const unsigned old = xb_add(&bar[XB_XSUB(b.x)], 1u);
;         const unsigned gen = old / nloc;
;         if (old + 1u == (gen + 1u) * nloc) {
;             __builtin_amdgcn_fence(__ATOMIC_RELEASE, "agent");
;             asm volatile("s_waitcnt vmcnt(0)" ::: "memory");
;             const unsigned og = xb_add(&bar[XB_TOP], 1u);
;             const unsigned tg = og / nx;
;             if (og + 1u == (tg + 1u) * nx) xb_add(&bar[XB_TOPGEN], 1u);
;             else XB_SPIN(xb_ld(&bar[XB_TOPGEN]) == tg, bar);
;             __builtin_amdgcn_fence(__ATOMIC_ACQUIRE, "agent");
;             xb_add(&bar[XB_XGEN(b.x)], 1u);
;             asm volatile("s_waitcnt vmcnt(0)" ::: "memory");
;         } else {
;             XB_SPIN(xb_ld(&bar[XB_XGEN(b.x)]) == gen, bar);
.LBB0_723:
	s_lshl_b32 s23, s18, 6
	s_add_i32 s92, s23, 0x500
	s_lshl_b64 s[4:5], s[92:93], 2
	s_add_u32 s4, s2, s4
	s_addc_u32 s5, s3, s5
	global_atomic_add v5, v35, v228, s[4:5] sc0
	v_cvt_f32_u32_e32 v3, v4
	v_sub_u32_e32 v6, 0, v4
	v_rcp_iflag_f32_e32 v3, v3
	s_nop 0
	v_mul_f32_e32 v3, 0x4f7ffffe, v3
	v_cvt_u32_f32_e32 v3, v3
	v_mul_lo_u32 v6, v6, v3
	v_mul_hi_u32 v6, v3, v6
	v_add_u32_e32 v3, v3, v6
	s_waitcnt vmcnt(0)
	buffer_inv sc1
	v_mul_hi_u32 v3, v5, v3
	v_mul_lo_u32 v6, v3, v4
	v_sub_u32_e32 v6, v5, v6
	v_add_u32_e32 v7, 1, v3
	v_cmp_ge_u32_e32 vcc, v6, v4
	v_add_u32_e32 v5, 1, v5
	s_nop 0
	v_cndmask_b32_e32 v3, v3, v7, vcc
	v_sub_u32_e32 v7, v6, v4
	v_cndmask_b32_e32 v6, v6, v7, vcc
	v_add_u32_e32 v7, 1, v3
	v_cmp_ge_u32_e32 vcc, v6, v4
	s_nop 1
	v_cndmask_b32_e32 v3, v3, v7, vcc
	v_mul_lo_u32 v6, v4, v3
	v_add_u32_e32 v4, v6, v4
	v_cmp_ne_u32_e32 vcc, v5, v4
	s_and_saveexec_b64 s[4:5], vcc
	s_xor_b64 s[4:5], exec, s[4:5]
	s_cbranch_execz .LBB0_737
	s_add_i32 s92, s23, 0x900
	s_lshl_b64 s[6:7], s[92:93], 2
	s_add_u32 s8, s2, s6
	s_addc_u32 s9, s3, s7
	s_waitcnt lgkmcnt(0)
	global_load_dword v2, v35, s[8:9] sc1
	s_waitcnt vmcnt(0)
	v_cmp_eq_u32_e32 vcc, v2, v3
	s_and_saveexec_b64 s[6:7], vcc
	s_cbranch_execz .LBB0_736
	s_mov_b32 s20, 1
	s_mov_b64 s[10:11], 0
	s_branch .LBB0_727

; __device__ __forceinline__ unsigned xb_ld(unsigned* p)              { return __hip_atomic_load(p, __ATOMIC_RELAXED, __HIP_MEMORY_SCOPE_AGENT); }
; #define XB_SPIN(cond, bar) do { unsigned _sp = 0; while (cond) { __builtin_amdgcn_s_sleep(1); \
;     if ((++_sp & 255u) == 0u) { if (xb_ld(&(bar)[XB_TMO])) break; if (_sp > XB_SPIN_CAP) { atomicAdd(&(bar)[XB_TMO], 1u); break; } } } } while (0)
; __device__ __forceinline__ void xcd_barrier(const XcdBarrier& b) {
;     ...
;             XB_SPIN(xb_ld(&bar[XB_XGEN(b.x)]) == gen, bar);
;             __builtin_amdgcn_fence(__ATOMIC_ACQUIRE, "agent");
;             asm volatile("s_waitcnt vmcnt(0)" ::: "memory");
.LBB0_736:
	s_or_b64 exec, exec, s[6:7]
	s_waitcnt vmcnt(0)
	s_waitcnt vmcnt(0)

; __device__ __forceinline__ unsigned xb_add(unsigned* p, unsigned v) { return __hip_atomic_fetch_add(p, v, __ATOMIC_RELAXED, __HIP_MEMORY_SCOPE_AGENT); }
; __device__ __forceinline__ void xcd_barrier(const XcdBarrier& b) {
;     ...
;             __builtin_amdgcn_fence(__ATOMIC_ACQUIRE, "agent");
;             xb_add(&bar[XB_XGEN(b.x)], 1u);
;             asm volatile("s_waitcnt vmcnt(0)" ::: "memory");
.LBB0_754:
	s_or_b64 exec, exec, s[4:5]
	s_add_i32 s92, s23, 0x900
	s_lshl_b64 s[4:5], s[92:93], 2
	s_add_u32 s2, s2, s4
	s_addc_u32 s3, s3, s5
	s_waitcnt vmcnt(0)
	global_atomic_add v35, v228, s[2:3]
	s_waitcnt vmcnt(0)

; __device__ __forceinline__ unsigned xb_ld(unsigned* p)              { return __hip_atomic_load(p, __ATOMIC_RELAXED, __HIP_MEMORY_SCOPE_AGENT); }
; __device__ __forceinline__ unsigned xb_add(unsigned* p, unsigned v) { return __hip_atomic_fetch_add(p, v, __ATOMIC_RELAXED, __HIP_MEMORY_SCOPE_AGENT); }
; #define XB_SPIN(cond, bar) do { unsigned _sp = 0; while (cond) { __builtin_amdgcn_s_sleep(1); \
;     if ((++_sp & 255u) == 0u) { if (xb_ld(&(bar)[XB_TMO])) break; if (_sp > XB_SPIN_CAP) { atomicAdd(&(bar)[XB_TMO], 1u); break; } } } } while (0)
; __device__ __forceinline__ void xcd_barrier(const XcdBarrier& b) {
;     ...
;         const unsigned old = xb_add(&bar[XB_XSUB(b.x)], 1u);
;         const unsigned gen = old / nloc;
;         if (old + 1u == (gen + 1u) * nloc) {
;             __builtin_amdgcn_fence(__ATOMIC_RELEASE, "agent");
;             asm volatile("s_waitcnt vmcnt(0)" ::: "memory");
;             const unsigned og = xb_add(&bar[XB_TOP], 1u);
;             const unsigned tg = og / nx;
;             if (og + 1u == (tg + 1u) * nx) xb_add(&bar[XB_TOPGEN], 1u);
;             else XB_SPIN(xb_ld(&bar[XB_TOPGEN]) == tg, bar);
;             __builtin_amdgcn_fence(__ATOMIC_ACQUIRE, "agent");
;             xb_add(&bar[XB_XGEN(b.x)], 1u);
;             asm volatile("s_waitcnt vmcnt(0)" ::: "memory");
;         } else {
;             XB_SPIN(xb_ld(&bar[XB_XGEN(b.x)]) == gen, bar);
.LBB0_990:
	s_lshl_b32 s25, s20, 6
	s_add_i32 s92, s25, 0x500
	s_lshl_b64 s[6:7], s[92:93], 2
	s_add_u32 s6, s4, s6
	s_addc_u32 s7, s5, s7
	global_atomic_add v5, v35, v228, s[6:7] sc0
	v_cvt_f32_u32_e32 v3, v4
	v_sub_u32_e32 v6, 0, v4
	v_rcp_iflag_f32_e32 v3, v3
	s_nop 0
	v_mul_f32_e32 v3, 0x4f7ffffe, v3
	v_cvt_u32_f32_e32 v3, v3
	v_mul_lo_u32 v6, v6, v3
	v_mul_hi_u32 v6, v3, v6
	v_add_u32_e32 v3, v3, v6
	s_waitcnt vmcnt(0)
	buffer_inv sc1
	v_mul_hi_u32 v3, v5, v3
	v_mul_lo_u32 v6, v3, v4
	v_sub_u32_e32 v6, v5, v6
	v_add_u32_e32 v7, 1, v3
	v_cmp_ge_u32_e32 vcc, v6, v4
	v_add_u32_e32 v5, 1, v5
	s_nop 0
	v_cndmask_b32_e32 v3, v3, v7, vcc
	v_sub_u32_e32 v7, v6, v4
	v_cndmask_b32_e32 v6, v6, v7, vcc
	v_add_u32_e32 v7, 1, v3
	v_cmp_ge_u32_e32 vcc, v6, v4
	s_nop 1
	v_cndmask_b32_e32 v3, v3, v7, vcc
	v_mul_lo_u32 v6, v4, v3
	v_add_u32_e32 v4, v6, v4
	v_cmp_ne_u32_e32 vcc, v5, v4
	s_and_saveexec_b64 s[6:7], vcc
	s_xor_b64 s[6:7], exec, s[6:7]
	s_cbranch_execz .LBB0_1004
	s_add_i32 s92, s25, 0x900
	s_lshl_b64 s[8:9], s[92:93], 2
	s_add_u32 s10, s4, s8
	s_addc_u32 s11, s5, s9
	s_waitcnt lgkmcnt(0)
	global_load_dword v2, v35, s[10:11] sc1
	s_waitcnt vmcnt(0)
	v_cmp_eq_u32_e32 vcc, v2, v3
	s_and_saveexec_b64 s[8:9], vcc
	s_cbranch_execz .LBB0_1003
	s_mov_b32 s22, 1
	s_mov_b64 s[12:13], 0
	s_branch .LBB0_994

; __device__ __forceinline__ unsigned xb_add(unsigned* p, unsigned v) { return __hip_atomic_fetch_add(p, v, __ATOMIC_RELAXED, __HIP_MEMORY_SCOPE_AGENT); }
; __device__ __forceinline__ void xcd_barrier(const XcdBarrier& b) {
;     ...
;             __builtin_amdgcn_fence(__ATOMIC_ACQUIRE, "agent");
;             xb_add(&bar[XB_XGEN(b.x)], 1u);
;             asm volatile("s_waitcnt vmcnt(0)" ::: "memory");
.LBB0_1021:
	s_or_b64 exec, exec, s[6:7]
	s_add_i32 s92, s25, 0x900
	s_lshl_b64 s[6:7], s[92:93], 2
	s_add_u32 s4, s4, s6
	s_addc_u32 s5, s5, s7
	s_waitcnt vmcnt(0)
	global_atomic_add v35, v228, s[4:5]
	s_waitcnt vmcnt(0)

; __device__ __forceinline__ unsigned xb_ld(unsigned* p)              { return __hip_atomic_load(p, __ATOMIC_RELAXED, __HIP_MEMORY_SCOPE_AGENT); }
; __device__ __forceinline__ unsigned xb_add(unsigned* p, unsigned v) { return __hip_atomic_fetch_add(p, v, __ATOMIC_RELAXED, __HIP_MEMORY_SCOPE_AGENT); }
; #define XB_SPIN(cond, bar) do { unsigned _sp = 0; while (cond) { __builtin_amdgcn_s_sleep(1); \
;     if ((++_sp & 255u) == 0u) { if (xb_ld(&(bar)[XB_TMO])) break; if (_sp > XB_SPIN_CAP) { atomicAdd(&(bar)[XB_TMO], 1u); break; } } } } while (0)
; __device__ __forceinline__ void xcd_barrier(const XcdBarrier& b) {
;     ...
;         const unsigned old = xb_add(&bar[XB_XSUB(b.x)], 1u);
;         const unsigned gen = old / nloc;
;         if (old + 1u == (gen + 1u) * nloc) {
;             __builtin_amdgcn_fence(__ATOMIC_RELEASE, "agent");
;             asm volatile("s_waitcnt vmcnt(0)" ::: "memory");
;             const unsigned og = xb_add(&bar[XB_TOP], 1u);
;             const unsigned tg = og / nx;
;             if (og + 1u == (tg + 1u) * nx) xb_add(&bar[XB_TOPGEN], 1u);
;             else XB_SPIN(xb_ld(&bar[XB_TOPGEN]) == tg, bar);
;             __builtin_amdgcn_fence(__ATOMIC_ACQUIRE, "agent");
;             xb_add(&bar[XB_XGEN(b.x)], 1u);
;             asm volatile("s_waitcnt vmcnt(0)" ::: "memory");
;         } else {
;             XB_SPIN(xb_ld(&bar[XB_XGEN(b.x)]) == gen, bar);
.LBB0_1568:
	s_lshl_b32 s24, s20, 6
	s_add_i32 s92, s24, 0x500
	s_lshl_b64 s[6:7], s[92:93], 2
	s_add_u32 s6, s2, s6
	s_addc_u32 s7, s3, s7
	global_atomic_add v5, v35, v228, s[6:7] sc0
	v_cvt_f32_u32_e32 v3, v4
	v_sub_u32_e32 v6, 0, v4
	v_rcp_iflag_f32_e32 v3, v3
	s_nop 0
	v_mul_f32_e32 v3, 0x4f7ffffe, v3
	v_cvt_u32_f32_e32 v3, v3
	v_mul_lo_u32 v6, v6, v3
	v_mul_hi_u32 v6, v3, v6
	v_add_u32_e32 v3, v3, v6
	s_waitcnt vmcnt(0)
	buffer_inv sc1
	v_mul_hi_u32 v3, v5, v3
	v_mul_lo_u32 v6, v3, v4
	v_sub_u32_e32 v6, v5, v6
	v_add_u32_e32 v7, 1, v3
	v_cmp_ge_u32_e32 vcc, v6, v4
	v_add_u32_e32 v5, 1, v5
	s_nop 0
	v_cndmask_b32_e32 v3, v3, v7, vcc
	v_sub_u32_e32 v7, v6, v4
	v_cndmask_b32_e32 v6, v6, v7, vcc
	v_add_u32_e32 v7, 1, v3
	v_cmp_ge_u32_e32 vcc, v6, v4
	s_nop 1
	v_cndmask_b32_e32 v3, v3, v7, vcc
	v_mul_lo_u32 v6, v4, v3
	v_add_u32_e32 v4, v6, v4
	v_cmp_ne_u32_e32 vcc, v5, v4
	s_and_saveexec_b64 s[6:7], vcc
	s_xor_b64 s[6:7], exec, s[6:7]
	s_cbranch_execz .LBB0_1582
	s_add_i32 s92, s24, 0x900
	s_lshl_b64 s[8:9], s[92:93], 2
	s_add_u32 s10, s2, s8
	s_addc_u32 s11, s3, s9
	s_waitcnt lgkmcnt(0)
	global_load_dword v2, v35, s[10:11] sc1
	s_waitcnt vmcnt(0)
	v_cmp_eq_u32_e32 vcc, v2, v3
	s_and_saveexec_b64 s[8:9], vcc
	s_cbranch_execz .LBB0_1581
	s_mov_b32 s22, 1
	s_mov_b64 s[12:13], 0
	s_branch .LBB0_1572

; __device__ __forceinline__ unsigned xb_add(unsigned* p, unsigned v) { return __hip_atomic_fetch_add(p, v, __ATOMIC_RELAXED, __HIP_MEMORY_SCOPE_AGENT); }
; __device__ __forceinline__ void xcd_barrier(const XcdBarrier& b) {
;     ...
;             __builtin_amdgcn_fence(__ATOMIC_ACQUIRE, "agent");
;             xb_add(&bar[XB_XGEN(b.x)], 1u);
;             asm volatile("s_waitcnt vmcnt(0)" ::: "memory");
.LBB0_1599:
	s_or_b64 exec, exec, s[6:7]
	s_add_i32 s92, s24, 0x900
	s_lshl_b64 s[6:7], s[92:93], 2
	s_add_u32 s2, s2, s6
	s_addc_u32 s3, s3, s7
	s_waitcnt vmcnt(0)
	global_atomic_add v35, v228, s[2:3]
	s_waitcnt vmcnt(0)

; __device__ __forceinline__ unsigned xb_ld(unsigned* p)              { return __hip_atomic_load(p, __ATOMIC_RELAXED, __HIP_MEMORY_SCOPE_AGENT); }
; __device__ __forceinline__ unsigned xb_add(unsigned* p, unsigned v) { return __hip_atomic_fetch_add(p, v, __ATOMIC_RELAXED, __HIP_MEMORY_SCOPE_AGENT); }
; #define XB_SPIN(cond, bar) do { unsigned _sp = 0; while (cond) { __builtin_amdgcn_s_sleep(1); \
;     if ((++_sp & 255u) == 0u) { if (xb_ld(&(bar)[XB_TMO])) break; if (_sp > XB_SPIN_CAP) { atomicAdd(&(bar)[XB_TMO], 1u); break; } } } } while (0)
; __device__ __forceinline__ void xcd_barrier(const XcdBarrier& b) {
;     ...
;         const unsigned old = xb_add(&bar[XB_XSUB(b.x)], 1u);
;         const unsigned gen = old / nloc;
;         if (old + 1u == (gen + 1u) * nloc) {
;             __builtin_amdgcn_fence(__ATOMIC_RELEASE, "agent");
;             asm volatile("s_waitcnt vmcnt(0)" ::: "memory");
;             const unsigned og = xb_add(&bar[XB_TOP], 1u);
;             const unsigned tg = og / nx;
;             if (og + 1u == (tg + 1u) * nx) xb_add(&bar[XB_TOPGEN], 1u);
;             else XB_SPIN(xb_ld(&bar[XB_TOPGEN]) == tg, bar);
;             __builtin_amdgcn_fence(__ATOMIC_ACQUIRE, "agent");
;             xb_add(&bar[XB_XGEN(b.x)], 1u);
;             asm volatile("s_waitcnt vmcnt(0)" ::: "memory");
;         } else {
;             XB_SPIN(xb_ld(&bar[XB_XGEN(b.x)]) == gen, bar);
.LBB0_2095:
	s_lshl_b32 s22, s18, 6
	s_add_i32 s92, s22, 0x500
	s_lshl_b64 s[4:5], s[92:93], 2
	s_add_u32 s4, s2, s4
	s_addc_u32 s5, s3, s5
	global_atomic_add v5, v35, v228, s[4:5] sc0
	v_cvt_f32_u32_e32 v3, v4
	v_sub_u32_e32 v6, 0, v4
	v_rcp_iflag_f32_e32 v3, v3
	s_nop 0
	v_mul_f32_e32 v3, 0x4f7ffffe, v3
	v_cvt_u32_f32_e32 v3, v3
	v_mul_lo_u32 v6, v6, v3
	v_mul_hi_u32 v6, v3, v6
	v_add_u32_e32 v3, v3, v6
	s_waitcnt vmcnt(0)
	buffer_inv sc1
	v_mul_hi_u32 v3, v5, v3
	v_mul_lo_u32 v6, v3, v4
	v_sub_u32_e32 v6, v5, v6
	v_add_u32_e32 v7, 1, v3
	v_cmp_ge_u32_e32 vcc, v6, v4
	v_add_u32_e32 v5, 1, v5
	s_nop 0
	v_cndmask_b32_e32 v3, v3, v7, vcc
	v_sub_u32_e32 v7, v6, v4
	v_cndmask_b32_e32 v6, v6, v7, vcc
	v_add_u32_e32 v7, 1, v3
	v_cmp_ge_u32_e32 vcc, v6, v4
	s_nop 1
	v_cndmask_b32_e32 v3, v3, v7, vcc
	v_mul_lo_u32 v6, v4, v3
	v_add_u32_e32 v4, v6, v4
	v_cmp_ne_u32_e32 vcc, v5, v4
	s_and_saveexec_b64 s[4:5], vcc
	s_xor_b64 s[4:5], exec, s[4:5]
	s_cbranch_execz .LBB0_2109
	s_add_i32 s92, s22, 0x900
	s_lshl_b64 s[6:7], s[92:93], 2
	s_add_u32 s8, s2, s6
	s_addc_u32 s9, s3, s7
	s_waitcnt lgkmcnt(0)
	global_load_dword v2, v35, s[8:9] sc1
	s_waitcnt vmcnt(0)
	v_cmp_eq_u32_e32 vcc, v2, v3
	s_and_saveexec_b64 s[6:7], vcc
	s_cbranch_execz .LBB0_2108
	s_mov_b32 s20, 1
	s_mov_b64 s[10:11], 0
	s_branch .LBB0_2099
